# v8 plus never-executed padding so every MFMA loop sits at the baseline's address mod 256 (code placement)
# speedup vs baseline: 1.0088x; 1.0088x over previous
; #define PG8_STAGE(bufoff, gbase, voff) do { _Pragma("unroll") for (int _i = 0; _i < 2; ++_i) \
;         __builtin_amdgcn_global_load_lds((const unsigned*)((const char*)(gbase) + (voff)[_i]), (LAS unsigned*)(lds + (bufoff) + ldsw + _i * 8192), 16, 0, 0); } while (0)
; #define PG8_WAIT_V(n) asm volatile("s_waitcnt vmcnt(" #n ")" ::: "memory")
; #define PG8_BAR __builtin_amdgcn_s_barrier()
; template <class Epi, class Sched>
; __device__ __forceinline__ void gemm_phase(LAS unsigned char* lds, const Gemm g, const Sched& S, const Epi& E) {
;     ...
;     const char* cA = (const char*)g.A + (size_t)cur.pm * tstepA + (size_t)cur.ka * 2; const char* cB = (const char*)g.Bt + (size_t)cur.pn * tstepB;
;     S.a_ready(cur);
;     PG8_STAGE(PG8_SB(0, 0), cB, voffB); PG8_STAGE(PG8_SB(0, 1), cB + hstepB, voffB); PG8_STAGE(PG8_SA(0, 0), cA, voffA); PG8_STAGE(PG8_SA(0, 1), cA + hstepA, voffA);
;     if (wr == 1) PG8_BAR;
;     PG8_WAIT_V(2); PG8_BAR;
;     PG8_STAGE(PG8_SB(1, 0), cB + kstep, voffB); PG8_STAGE(PG8_SA(1, 0), cA + kstep, voffA); PG8_STAGE(PG8_SB(1, 1), cB + hstepB + kstep, voffB);
;     PG8_WAIT_V(6); PG8_BAR;
;     for (;;) {
;         const bool has_next = S.next(ui + 1, nxt);
;         const char* nA = has_next ? (const char*)g.A + (size_t)nxt.pm * tstepA + (size_t)nxt.ka * 2 : cA; const char* nB = has_next ? (const char*)g.Bt + (size_t)nxt.pn * tstepB : cB;
;         for (int t = 0; t < nt; t += 2) {
.Lmy_rsfill_done:
	s_or_b64 exec, exec, s[100:101]
	s_mov_b32 s100, s54
	s_waitcnt lgkmcnt(0)
	s_barrier
	v_readlane_b32 s19, v253, 54
	s_branch .LBB0_134
	s_nop 0
	s_nop 0
	s_nop 0
	s_nop 0
	s_nop 0
	s_nop 0
	s_nop 0
	s_nop 0
	s_nop 0
	s_nop 0
	s_nop 0
	s_nop 0
	s_nop 0
	s_nop 0
	s_nop 0
	s_nop 0
	s_nop 0
	s_nop 0
	s_nop 0
	s_nop 0
	s_nop 0
	s_nop 0
	s_nop 0
	s_nop 0
	s_nop 0
	s_nop 0
	s_nop 0
	s_nop 0
	s_nop 0
	s_nop 0
	s_nop 0
	s_nop 0
	s_nop 0
	s_nop 0
	s_nop 0

; #define PG8_STAGE(bufoff, gbase, voff) do { _Pragma("unroll") for (int _i = 0; _i < 2; ++_i) \
;         __builtin_amdgcn_global_load_lds((const unsigned*)((const char*)(gbase) + (voff)[_i]), (LAS unsigned*)(lds + (bufoff) + ldsw + _i * 8192), 16, 0, 0); } while (0)
; #define PG8_WAIT_V(n) asm volatile("s_waitcnt vmcnt(" #n ")" ::: "memory")
; #define PG8_BAR __builtin_amdgcn_s_barrier()
; template <class Epi, class Sched>
; __device__ __forceinline__ void gemm_phase(LAS unsigned char* lds, const Gemm g, const Sched& S, const Epi& E) {
;     ...
;     f32x4 acc[2][2][4][2];
; #pragma unroll
;     for (int a = 0; a < 2; ++a)
; #pragma unroll
;         for (int b = 0; b < 2; ++b)
; #pragma unroll
;             for (int m = 0; m < 4; ++m)
; #pragma unroll
;                 for (int n = 0; n < 2; ++n) acc[a][b][m][n] = (f32x4){0.f, 0.f, 0.f, 0.f};
;     bf16x8 At[4][2], B0[2][2], B1[2][2];
;     const char* cA = (const char*)g.A + (size_t)cur.pm * tstepA + (size_t)cur.ka * 2; const char* cB = (const char*)g.Bt + (size_t)cur.pn * tstepB;
;     S.a_ready(cur);
;     PG8_STAGE(PG8_SB(0, 0), cB, voffB); PG8_STAGE(PG8_SB(0, 1), cB + hstepB, voffB); PG8_STAGE(PG8_SA(0, 0), cA, voffA); PG8_STAGE(PG8_SA(0, 1), cA + hstepA, voffA);
;     if (wr == 1) PG8_BAR;
;     PG8_WAIT_V(2); PG8_BAR;
;     PG8_STAGE(PG8_SB(1, 0), cB + kstep, voffB); PG8_STAGE(PG8_SA(1, 0), cA + kstep, voffA); PG8_STAGE(PG8_SB(1, 1), cB + hstepB + kstep, voffB);
;     PG8_WAIT_V(6); PG8_BAR;
.LBB0_267:
	v_lshl_add_u64 v[14:15], s[24:25], 0, v[4:5]
	v_mov_b32_e32 v3, v5
	v_and_b32_e32 v142, 15, v143
	v_and_b32_e32 v22, 48, v143
	v_lshlrev_b32_e32 v23, 2, v143
	v_lshl_add_u64 v[16:17], s[24:25], 0, v[2:3]
	s_and_b32 s48, s44, 3
	v_lshl_or_b32 v22, v142, 6, v22
	s_lshl_b32 s4, s47, 13
	v_and_b32_e32 v23, 32, v23
	s_add_i32 m0, s50, 0x18000
	v_lshl_add_u64 v[14:15], v[14:15], 0, s[36:37]
	v_lshl_add_u64 v[18:19], s[20:21], 0, v[4:5]
	v_bitop3_b32 v24, v22, s4, v23 bitop3:0xde
	s_lshl_b32 s4, s48, 12
	s_waitcnt vmcnt(2)
	s_barrier
	global_load_lds_dwordx4 v[14:15], off
	v_lshl_add_u64 v[14:15], v[16:17], 0, s[36:37]
	s_add_i32 m0, s50, 0x1a000
	s_add_i32 s54, s50, 0x8000
	s_add_i32 s55, s50, 0xa000
	v_lshl_add_u64 v[20:21], s[20:21], 0, v[2:3]
	v_bitop3_b32 v144, v22, s4, v23 bitop3:0xde
	global_load_lds_dwordx4 v[14:15], off
	v_lshl_add_u64 v[14:15], v[18:19], 0, s[36:37]
	s_mov_b32 m0, s54
	s_add_u32 s4, s24, 0x158080
	global_load_lds_dwordx4 v[14:15], off
	v_lshl_add_u64 v[14:15], v[20:21], 0, s[36:37]
	s_mov_b32 m0, s55
	s_addc_u32 s5, s25, 0
	global_load_lds_dwordx4 v[14:15], off
	s_add_i32 m0, s50, 0x1c000
	v_lshl_add_u64 v[14:15], s[4:5], 0, v[4:5]
	global_load_lds_dwordx4 v[14:15], off
	v_lshl_add_u64 v[14:15], s[4:5], 0, v[2:3]
	s_add_i32 m0, s50, 0x1e000
	s_movk_i32 s10, 0x1580
	global_load_lds_dwordx4 v[14:15], off
	v_lshrrev_b32_e32 v11, 1, v11
	v_mul_lo_u32 v10, v10, s10
	s_mov_b32 s22, 0x15800
	v_mad_u64_u32 v[10:11], s[4:5], v11, s22, v[10:11]
	v_or_b32_e32 v10, v10, v12
	v_add_lshl_u32 v134, v10, v13, 1
	v_lshrrev_b32_e32 v10, 1, v6
	v_mul_lo_u32 v6, v7, s10
	v_mad_u64_u32 v[6:7], s[4:5], v10, s22, v[6:7]
	s_waitcnt vmcnt(6)
	v_or_b32_e32 v6, v6, v8
	s_cmpk_lt_u32 s45, 0x100
	v_add_lshl_u32 v136, v6, v9, 1
	v_mov_b32_e32 v6, 0
	v_readlane_b32 s4, v254, 13
	s_cselect_b64 s[18:19], -1, 0
	v_mov_b32_e32 v135, v5
	v_mov_b32_e32 v137, v5
	s_mov_b32 s59, 0
	v_add_u32_e32 v145, 0, v24
	s_mov_b32 s10, s4
	v_readlane_b32 s46, v253, 61
	v_mov_b32_e32 v7, v6
	v_mov_b32_e32 v8, v6
	v_mov_b32_e32 v9, v6
	v_mov_b32_e32 v10, v6
	v_mov_b32_e32 v11, v6
	v_mov_b32_e32 v12, v6
	v_mov_b32_e32 v13, v6
	v_mov_b32_e32 v14, v6
	v_mov_b32_e32 v15, v6
	v_mov_b32_e32 v16, v6
	v_mov_b32_e32 v17, v6
	v_mov_b32_e32 v18, v6
	v_mov_b32_e32 v19, v6
	v_mov_b32_e32 v20, v6
	v_mov_b32_e32 v21, v6
	v_mov_b32_e32 v22, v6
	v_mov_b32_e32 v23, v6
	v_mov_b32_e32 v24, v6
	v_mov_b32_e32 v25, v6
	v_mov_b32_e32 v30, v6
	v_mov_b32_e32 v31, v6
	v_mov_b32_e32 v32, v6
	v_mov_b32_e32 v33, v6
	v_mov_b32_e32 v38, v6
	v_mov_b32_e32 v39, v6
	v_mov_b32_e32 v40, v6
	v_mov_b32_e32 v41, v6
	v_mov_b32_e32 v46, v6
	v_mov_b32_e32 v47, v6
	v_mov_b32_e32 v48, v6
	v_mov_b32_e32 v49, v6
	v_mov_b32_e32 v26, v6
	v_mov_b32_e32 v27, v6
	v_mov_b32_e32 v28, v6
	v_mov_b32_e32 v29, v6
	v_mov_b32_e32 v34, v6
	v_mov_b32_e32 v35, v6
	v_mov_b32_e32 v36, v6
	v_mov_b32_e32 v37, v6
	v_mov_b32_e32 v42, v6
	v_mov_b32_e32 v43, v6
	v_mov_b32_e32 v44, v6
	v_mov_b32_e32 v45, v6
	v_mov_b32_e32 v50, v6
	v_mov_b32_e32 v51, v6
	v_mov_b32_e32 v52, v6
	v_mov_b32_e32 v53, v6
	v_mov_b32_e32 v54, v6
	v_mov_b32_e32 v55, v6
	v_mov_b32_e32 v56, v6
	v_mov_b32_e32 v57, v6
	v_mov_b32_e32 v58, v6
	v_mov_b32_e32 v59, v6
	v_mov_b32_e32 v60, v6
	v_mov_b32_e32 v61, v6
	v_mov_b32_e32 v62, v6
	v_mov_b32_e32 v63, v6
	v_mov_b32_e32 v64, v6
	v_mov_b32_e32 v65, v6
	v_mov_b32_e32 v66, v6
	v_mov_b32_e32 v67, v6
	v_mov_b32_e32 v68, v6
	v_mov_b32_e32 v69, v6
	v_mov_b32_e32 v70, v6
	v_mov_b32_e32 v71, v6
	v_mov_b32_e32 v72, v6
	v_mov_b32_e32 v73, v6
	v_mov_b32_e32 v74, v6
	v_mov_b32_e32 v75, v6
	v_mov_b32_e32 v76, v6
	v_mov_b32_e32 v77, v6
	v_mov_b32_e32 v78, v6
	v_mov_b32_e32 v79, v6
	v_mov_b32_e32 v80, v6
	v_mov_b32_e32 v81, v6
	v_mov_b32_e32 v82, v6
	v_mov_b32_e32 v83, v6
	v_mov_b32_e32 v84, v6
	v_mov_b32_e32 v85, v6
	v_mov_b32_e32 v86, v6
	v_mov_b32_e32 v87, v6
	v_mov_b32_e32 v88, v6
	v_mov_b32_e32 v89, v6
	v_mov_b32_e32 v94, v6
	v_mov_b32_e32 v95, v6
	v_mov_b32_e32 v96, v6
	v_mov_b32_e32 v97, v6
	v_mov_b32_e32 v102, v6
	v_mov_b32_e32 v103, v6
	v_mov_b32_e32 v104, v6
	v_mov_b32_e32 v105, v6
	v_mov_b32_e32 v114, v6
	v_mov_b32_e32 v115, v6
	v_mov_b32_e32 v116, v6
	v_mov_b32_e32 v117, v6
	v_mov_b32_e32 v90, v6
	v_mov_b32_e32 v91, v6
	v_mov_b32_e32 v92, v6
	v_mov_b32_e32 v93, v6
	v_mov_b32_e32 v98, v6
	v_mov_b32_e32 v99, v6
	v_mov_b32_e32 v100, v6
	v_mov_b32_e32 v101, v6
	v_mov_b32_e32 v106, v6
	v_mov_b32_e32 v107, v6
	v_mov_b32_e32 v108, v6
	v_mov_b32_e32 v109, v6
	v_mov_b32_e32 v110, v6
	v_mov_b32_e32 v111, v6
	v_mov_b32_e32 v112, v6
	v_mov_b32_e32 v113, v6
	v_mov_b32_e32 v118, v6
	v_mov_b32_e32 v119, v6
	v_mov_b32_e32 v120, v6
	v_mov_b32_e32 v121, v6
	v_mov_b32_e32 v122, v6
	v_mov_b32_e32 v123, v6
	v_mov_b32_e32 v124, v6
	v_mov_b32_e32 v125, v6
	v_mov_b32_e32 v126, v6
	v_mov_b32_e32 v127, v6
	v_mov_b32_e32 v128, v6
	v_mov_b32_e32 v129, v6
	v_mov_b32_e32 v130, v6
	v_mov_b32_e32 v131, v6
	v_mov_b32_e32 v132, v6
	v_mov_b32_e32 v133, v6
	s_barrier
	s_branch .LBB0_270
	s_nop 0
	s_nop 0
	s_nop 0
	s_nop 0
	s_nop 0
	s_nop 0
	s_nop 0
	s_nop 0
	s_nop 0
	s_nop 0
	s_nop 0
	s_nop 0
	s_nop 0
	s_nop 0
	s_nop 0
	s_nop 0
	s_nop 0
	s_nop 0
	s_nop 0
	s_nop 0
	s_nop 0
	s_nop 0
	s_nop 0
	s_nop 0
	s_nop 0
	s_nop 0
	s_nop 0
	s_nop 0
	s_nop 0
	s_nop 0

; #define PG8_STAGE(bufoff, gbase, voff) do { _Pragma("unroll") for (int _i = 0; _i < 2; ++_i) \
;         __builtin_amdgcn_global_load_lds((const unsigned*)((const char*)(gbase) + (voff)[_i]), (LAS unsigned*)(lds + (bufoff) + ldsw + _i * 8192), 16, 0, 0); } while (0)
; #define PG8_WAIT_V(n) asm volatile("s_waitcnt vmcnt(" #n ")" ::: "memory")
; #define PG8_BAR __builtin_amdgcn_s_barrier()
; template <class Epi, class Sched>
; __device__ __forceinline__ void gemm_phase(LAS unsigned char* lds, const Gemm g, const Sched& S, const Epi& E) {
;     ...
;     const char* cA = (const char*)g.A + (size_t)cur.pm * tstepA + (size_t)cur.ka * 2; const char* cB = (const char*)g.Bt + (size_t)cur.pn * tstepB;
;     S.a_ready(cur);
;     PG8_STAGE(PG8_SB(0, 0), cB, voffB); PG8_STAGE(PG8_SB(0, 1), cB + hstepB, voffB); PG8_STAGE(PG8_SA(0, 0), cA, voffA); PG8_STAGE(PG8_SA(0, 1), cA + hstepA, voffA);
;     if (wr == 1) PG8_BAR;
;     PG8_WAIT_V(2); PG8_BAR;
;     PG8_STAGE(PG8_SB(1, 0), cB + kstep, voffB); PG8_STAGE(PG8_SA(1, 0), cA + kstep, voffA); PG8_STAGE(PG8_SB(1, 1), cB + hstepB + kstep, voffB);
;     PG8_WAIT_V(6); PG8_BAR;
.LBB0_507:
	v_lshrrev_b32_e32 v20, 1, v4
	v_and_b32_e32 v20, 24, v20
	v_and_b32_e32 v21, 15, v4
	v_lshlrev_b32_e32 v22, 1, v20
	v_lshlrev_b32_e32 v4, 2, v4
	s_and_b32 s20, s17, 3
	v_lshl_or_b32 v235, s18, 6, v21
	v_lshl_or_b32 v21, v21, 6, v22
	s_lshl_b32 s17, s18, 13
	v_and_b32_e32 v4, 32, v4
	s_add_i32 m0, s50, 0x18000
	v_lshl_add_u64 v[12:13], v[12:13], 0, s[36:37]
	v_bitop3_b32 v22, v21, s17, v4 bitop3:0xde
	s_lshl_b32 s17, s20, 12
	s_waitcnt vmcnt(2)
	s_barrier
	global_load_lds_dwordx4 v[12:13], off
	v_lshl_add_u64 v[10:11], v[10:11], 0, s[36:37]
	s_add_i32 m0, s50, 0x1a000
	s_add_i32 s54, s50, 0x8000
	s_add_i32 s55, s50, 0xa000
	global_load_lds_dwordx4 v[10:11], off
	v_lshl_add_u64 v[6:7], v[6:7], 0, s[36:37]
	s_mov_b32 m0, s54
	s_add_u32 s18, s42, 0x80080
	global_load_lds_dwordx4 v[6:7], off
	v_lshl_add_u64 v[6:7], v[8:9], 0, s[36:37]
	s_mov_b32 m0, s55
	s_addc_u32 s19, s43, 0
	global_load_lds_dwordx4 v[6:7], off
	s_add_i32 m0, s50, 0x1c000
	v_lshl_add_u64 v[6:7], s[18:19], 0, v[212:213]
	global_load_lds_dwordx4 v[6:7], off
	v_lshl_add_u64 v[6:7], s[18:19], 0, v[216:217]
	s_add_i32 m0, s50, 0x1e000
	v_bitop3_b32 v236, v21, s17, v4 bitop3:0xde
	global_load_lds_dwordx4 v[6:7], off
	v_lshlrev_b32_e32 v4, 2, v20
	v_lshl_add_u64 v[218:219], s[12:13], 0, v[4:5]
	v_lshl_add_u64 v[220:221], s[10:11], 0, v[4:5]
	v_lshl_add_u64 v[222:223], s[14:15], 0, v[4:5]
	v_lshlrev_b32_e32 v4, 15, v14
	v_and_b32_e32 v4, 0xffff0000, v4
	v_lshl_add_u32 v4, v15, 12, v4
	v_and_b32_e32 v6, 1, v14
	v_lshl_or_b32 v4, v6, 6, v4
	v_lshl_add_u32 v224, v16, 1, v4
	v_lshlrev_b32_e32 v4, 15, v17
	v_and_b32_e32 v4, 0xffff0000, v4
	s_waitcnt vmcnt(6)
	v_lshl_add_u32 v4, v18, 12, v4
	v_and_b32_e32 v6, 1, v17
	s_cmpk_lt_u32 s16, 0x100
	v_lshl_or_b32 v4, v6, 6, v4
	s_cselect_b64 s[16:17], -1, 0
	s_lshl_b32 s56, s20, 6
	v_mov_b32_e32 v225, v5
	v_lshl_add_u32 v226, v19, 1, v4
	v_mov_b32_e32 v227, v5
	s_mov_b32 s57, 0
	v_add_u32_e32 v237, 0, v22
	v_lshlrev_b32_e32 v4, 1, v20
	s_barrier
	s_branch .LBB0_510
	s_nop 0
	s_nop 0
